# v34: on top of v31, the grid-size scalar load of the RG-LRU loop top is requested in the previous task's look-back window (its latency no longer sits in front of the prefetch / publish path)
# baseline (speedup 1.0000x reference)
.LBB0_307:
	s_and_b32 s41, s40, 7
	s_cmp_eq_u32 s41, s2
	s_cbranch_scc1 .LBB0_309
	s_lshl_b32 s0, s41, 6
	v_or_b32_e32 v18, s0, v121
	s_mov_b64 s[42:43], s[52:53]
	v_readlane_b32 s52, v254, 60
	v_lshlrev_b32_e32 v38, 2, v18
	v_mov_b32_e32 v39, v196
	v_readlane_b32 s64, v255, 8
	v_readlane_b32 s65, v255, 9
	v_readlane_b32 s53, v254, 61
	v_readlane_b32 s54, v254, 62
	v_readlane_b32 s55, v254, 63
	v_readlane_b32 s56, v255, 0
	v_readlane_b32 s57, v255, 1
	v_readlane_b32 s58, v255, 2
	v_readlane_b32 s59, v255, 3
	v_readlane_b32 s60, v255, 4
	v_readlane_b32 s61, v255, 5
	v_readlane_b32 s62, v255, 6
	v_readlane_b32 s63, v255, 7
	v_readlane_b32 s66, v255, 10
	v_readlane_b32 s67, v255, 11
	v_lshl_add_u64 v[50:51], s[64:65], 0, v[38:39]
	s_mov_b64 s[16:17], 0x1000
	s_movk_i32 s1, 0x1000
	s_nop 1
	global_load_dwordx4 v[22:25], v38, s[66:67] offset:16
	global_load_dwordx4 v[18:21], v38, s[64:65] offset:16
	global_load_dwordx4 v[30:33], v38, s[66:67]
	global_load_dwordx4 v[26:29], v38, s[64:65]
	global_load_dwordx4 v[34:37], v38, s[64:65] offset:2064
	s_nop 0
	global_load_dwordx4 v[38:41], v38, s[64:65] offset:2048
	v_lshl_add_u64 v[42:43], v[50:51], 0, s[16:17]
	v_add_co_u32_e32 v52, vcc, s1, v50
	s_mov_b64 s[16:17], 0x1800
	v_or_b32_e32 v58, s0, v120
	v_readlane_b32 s52, v255, 12
	v_readlane_b32 s0, v255, 43
	v_addc_co_u32_e32 v53, vcc, 0, v51, vcc
	v_lshl_add_u64 v[50:51], v[50:51], 0, s[16:17]
	v_lshlrev_b32_e32 v58, 2, v58
	v_readlane_b32 s54, v255, 14
	v_readlane_b32 s55, v255, 15
	v_readlane_b32 s1, v255, 44
	global_load_dwordx4 v[46:49], v[52:53], off
	s_nop 0
	global_load_dwordx4 v[42:45], v[42:43], off offset:16
	s_nop 0
	global_load_dwordx4 v[54:57], v[52:53], off offset:2048
	s_nop 0
	global_load_dwordx4 v[50:53], v[50:51], off offset:16
	v_readlane_b32 s58, v255, 18
	v_readlane_b32 s59, v255, 19
	global_load_dword v153, v58, s[54:55]
	s_nop 3
	global_load_dword v154, v58, s[58:59]
	global_load_dword v155, v58, s[0:1]
	s_lshl_b32 s0, s41, 13
	s_mov_b32 s1, s46
	v_lshl_add_u64 v[74:75], v[96:97], 0, s[0:1]
	global_load_dwordx4 v[70:73], v[74:75], off
	global_load_dwordx4 v[66:69], v[74:75], off offset:64
	global_load_dwordx4 v[62:65], v[74:75], off offset:2048
	global_load_dwordx4 v[58:61], v[74:75], off offset:2112
	v_add_co_u32_e32 v74, vcc, 0x1000, v74
	v_readlane_b32 s60, v255, 20
	s_nop 0
	v_addc_co_u32_e32 v75, vcc, 0, v75, vcc
	global_load_dwordx4 v[86:89], v[74:75], off
	global_load_dwordx4 v[82:85], v[74:75], off offset:64
	global_load_dwordx4 v[78:81], v[74:75], off offset:2048
	s_nop 0
	global_load_dwordx4 v[74:77], v[74:75], off offset:2112
	v_readlane_b32 s61, v255, 21
	v_readlane_b32 s62, v255, 22
	v_readlane_b32 s63, v255, 23
	v_readlane_b32 s53, v255, 13
	v_readlane_b32 s62, v255, 51
	v_readlane_b32 s60, v255, 49
	s_mov_b64 s[52:53], s[42:43]
	v_readlane_b32 s63, v255, 52
	v_readlane_b32 s61, v255, 50
	s_mov_b32 s2, s41
	v_readlane_b32 s56, v255, 16
	v_readlane_b32 s57, v255, 17
	v_readlane_b32 s64, v255, 24
	v_readlane_b32 s65, v255, 25
	v_readlane_b32 s66, v255, 26
	v_readlane_b32 s67, v255, 27
	s_waitcnt vmcnt(0)
	s_barrier
	s_load_dword s77, s[78:79], 0x0
	v_lshlrev_b32_e32 v98, 16, v6
	v_and_b32_e32 v99, 0xffff0000, v6
	v_pk_fma_f32 v[98:99], v[26:27], v[98:99], v[30:31]
	v_lshlrev_b32_e32 v100, 16, v2
	v_and_b32_e32 v101, 0xffff0000, v2
	v_pk_fma_f32 v[98:99], v[38:39], v[100:101], v[98:99]
	v_lshlrev_b32_e32 v100, 16, v10
	v_and_b32_e32 v101, 0xffff0000, v10
	v_pk_fma_f32 v[98:99], v[46:47], v[100:101], v[98:99]
	v_lshlrev_b32_e32 v100, 16, v14
	v_and_b32_e32 v101, 0xffff0000, v14
	v_pk_fma_f32 v[98:99], v[54:55], v[100:101], v[98:99]
	v_lshlrev_b32_e32 v100, 16, v7
	v_and_b32_e32 v101, 0xffff0000, v7
	v_pk_fma_f32 v[100:101], v[28:29], v[100:101], v[32:33]
	v_lshlrev_b32_e32 v102, 16, v3
	v_and_b32_e32 v103, 0xffff0000, v3
	v_pk_fma_f32 v[100:101], v[40:41], v[102:103], v[100:101]
	v_lshlrev_b32_e32 v102, 16, v11
	v_and_b32_e32 v103, 0xffff0000, v11
	v_pk_fma_f32 v[100:101], v[48:49], v[102:103], v[100:101]
	v_lshlrev_b32_e32 v102, 16, v15
	v_and_b32_e32 v103, 0xffff0000, v15
	v_pk_fma_f32 v[100:101], v[56:57], v[102:103], v[100:101]
	v_lshlrev_b32_e32 v102, 16, v8
	v_and_b32_e32 v103, 0xffff0000, v8
	v_pk_fma_f32 v[102:103], v[18:19], v[102:103], v[22:23]
	v_lshlrev_b32_e32 v104, 16, v4
	v_and_b32_e32 v105, 0xffff0000, v4
	v_pk_fma_f32 v[102:103], v[34:35], v[104:105], v[102:103]
	v_lshlrev_b32_e32 v104, 16, v12
	v_and_b32_e32 v105, 0xffff0000, v12
	v_pk_fma_f32 v[102:103], v[42:43], v[104:105], v[102:103]
	v_lshlrev_b32_e32 v104, 16, v16
	v_and_b32_e32 v105, 0xffff0000, v16
	v_pk_fma_f32 v[102:103], v[50:51], v[104:105], v[102:103]
	v_lshlrev_b32_e32 v104, 16, v9
	v_and_b32_e32 v105, 0xffff0000, v9
	v_pk_fma_f32 v[104:105], v[20:21], v[104:105], v[24:25]
	v_lshlrev_b32_e32 v106, 16, v5
	v_and_b32_e32 v107, 0xffff0000, v5
	v_pk_fma_f32 v[104:105], v[36:37], v[106:107], v[104:105]
	v_lshlrev_b32_e32 v106, 16, v13
	v_and_b32_e32 v107, 0xffff0000, v13
	v_pk_fma_f32 v[104:105], v[44:45], v[106:107], v[104:105]
	v_lshlrev_b32_e32 v106, 16, v17
	v_and_b32_e32 v107, 0xffff0000, v17
	v_pk_fma_f32 v[104:105], v[52:53], v[106:107], v[104:105]
	v_cvt_pk_bf16_f32 v106, v98, v99
	v_cvt_pk_bf16_f32 v107, v100, v101
	v_cvt_pk_bf16_f32 v108, v102, v103
	v_add_u32_e32 v110, v122, v90
	v_cvt_pk_bf16_f32 v109, v104, v105
	ds_write_b128 v110, v[106:109]
	ds_write_b128 v123, v[98:101] offset:9216
	ds_write_b128 v123, v[102:105] offset:9232
.LBB0_309:
	s_waitcnt lgkmcnt(0)
	s_add_i32 s15, s77, s40
	s_cmpk_gt_i32 s15, 0x7ff
	s_cselect_b64 s[16:17], -1, 0
	s_and_b64 vcc, exec, s[16:17]
	s_cbranch_vccnz .LBB0_319
	s_lshl_b32 s0, s15, 8
	s_and_b32 s42, s15, 0xffffffc0
	s_and_b32 s33, s0, 0x3800
	s_lshl_b32 s0, s15, 7
	v_add_u32_e32 v14, s42, v124
	s_and_b32 s0, s0, 0x380
	s_mov_b32 s1, s46
	v_mov_b32_e32 v2, v196
	v_mov_b32_e32 v3, v196
	v_lshl_add_u64 v[98:99], v[92:93], 0, s[0:1]
	v_cmp_lt_i32_e32 vcc, -1, v14
	v_mov_b64_e32 v[6:7], v[2:3]
	v_mov_b64_e32 v[8:9], v[2:3]
	s_and_saveexec_b64 s[0:1], vcc
	s_cbranch_execz .LBB0_312
	v_add_u32_e32 v4, s33, v14
	s_movk_i32 s43, 0xc00
	v_mad_u64_u32 v[4:5], s[44:45], v4, s43, v[98:99]
	global_load_dwordx4 v[6:9], v[4:5], off

.LBB0_331:
	v_fmac_f32_e32 v115, v114, v117
	v_mul_f32_e32 v177, v114, v178
	s_and_saveexec_b64 s[0:1], s[52:53]
	s_cbranch_execz .LBB0_340
	s_add_i32 s68, s73, s33
	s_ashr_i32 s69, s68, 31
	s_lshl_b64 s[68:69], s[68:69], 12
	s_add_u32 s68, s36, s68
	v_or_b32_e32 v114, 1, v177
	s_addc_u32 s69, s37, s69
	global_store_dwordx2 v112, v[114:115], s[68:69] sc1
	s_or_b64 exec, exec, s[0:1]
	s_waitcnt vmcnt(1)
	v_lshlrev_b32_e32 v179, 16, v101
	v_mul_f32_e32 v222, 0x3d372713, v179
	v_mul_f32_e32 v222, v222, v179
	v_fma_f32 v222, v222, v179, v179
	v_mul_f32_e32 v222, 0x3f4c422a, v222
	v_add_f32_e32 v222, v222, v222
	v_mul_f32_e32 v222, 0x3fb8aa3b, v222
	v_exp_f32_e32 v222, v222
	v_mul_f32_e32 v179, 0.5, v179
	v_add_f32_e32 v222, 1.0, v222
	v_rcp_f32_e32 v222, v222
	s_nop 0
	v_fma_f32 v222, v222, -2.0, 1.0
	v_add_f32_e32 v222, 1.0, v222
	v_mul_f32_e32 v188, v179, v222
	v_lshlrev_b32_e32 v179, 16, v162
	v_mul_f32_e32 v222, 0x3d372713, v179
	v_mul_f32_e32 v222, v222, v179
	v_fma_f32 v222, v222, v179, v179
	v_mul_f32_e32 v222, 0x3f4c422a, v222
	v_add_f32_e32 v222, v222, v222
	v_mul_f32_e32 v222, 0x3fb8aa3b, v222
	v_exp_f32_e32 v222, v222
	v_mul_f32_e32 v179, 0.5, v179
	v_add_f32_e32 v222, 1.0, v222
	v_rcp_f32_e32 v222, v222
	s_nop 0
	v_fma_f32 v222, v222, -2.0, 1.0
	v_add_f32_e32 v222, 1.0, v222
	v_mul_f32_e32 v189, v179, v222
	v_lshlrev_b32_e32 v179, 16, v161
	v_mul_f32_e32 v222, 0x3d372713, v179
	v_mul_f32_e32 v222, v222, v179
	v_fma_f32 v222, v222, v179, v179
	v_mul_f32_e32 v222, 0x3f4c422a, v222
	v_add_f32_e32 v222, v222, v222
	v_mul_f32_e32 v222, 0x3fb8aa3b, v222
	v_exp_f32_e32 v222, v222
	v_mul_f32_e32 v179, 0.5, v179
	v_add_f32_e32 v222, 1.0, v222
	v_rcp_f32_e32 v222, v222
	s_nop 0
	v_fma_f32 v222, v222, -2.0, 1.0
	v_add_f32_e32 v222, 1.0, v222
	v_mul_f32_e32 v190, v179, v222
	v_lshlrev_b32_e32 v179, 16, v160
	v_mul_f32_e32 v222, 0x3d372713, v179
	v_mul_f32_e32 v222, v222, v179
	v_fma_f32 v222, v222, v179, v179
	v_mul_f32_e32 v222, 0x3f4c422a, v222
	v_add_f32_e32 v222, v222, v222
	v_mul_f32_e32 v222, 0x3fb8aa3b, v222
	v_exp_f32_e32 v222, v222
	v_mul_f32_e32 v179, 0.5, v179
	v_add_f32_e32 v222, 1.0, v222
	v_rcp_f32_e32 v222, v222
	s_nop 0
	v_fma_f32 v222, v222, -2.0, 1.0
	v_add_f32_e32 v222, 1.0, v222
	v_mul_f32_e32 v191, v179, v222
	v_lshlrev_b32_e32 v179, 16, v159
	v_mul_f32_e32 v222, 0x3d372713, v179
	v_mul_f32_e32 v222, v222, v179
	v_fma_f32 v222, v222, v179, v179
	v_mul_f32_e32 v222, 0x3f4c422a, v222
	v_add_f32_e32 v222, v222, v222
	v_mul_f32_e32 v222, 0x3fb8aa3b, v222
	v_exp_f32_e32 v222, v222
	v_mul_f32_e32 v179, 0.5, v179
	v_add_f32_e32 v222, 1.0, v222
	v_rcp_f32_e32 v222, v222
	s_nop 0
	v_fma_f32 v222, v222, -2.0, 1.0
	v_add_f32_e32 v222, 1.0, v222
	v_mul_f32_e32 v192, v179, v222
	v_lshlrev_b32_e32 v179, 16, v158
	v_mul_f32_e32 v222, 0x3d372713, v179
	v_mul_f32_e32 v222, v222, v179
	v_fma_f32 v222, v222, v179, v179
	v_mul_f32_e32 v222, 0x3f4c422a, v222
	v_add_f32_e32 v222, v222, v222
	v_mul_f32_e32 v222, 0x3fb8aa3b, v222
	v_exp_f32_e32 v222, v222
	v_mul_f32_e32 v179, 0.5, v179
	v_add_f32_e32 v222, 1.0, v222
	v_rcp_f32_e32 v222, v222
	s_nop 0
	v_fma_f32 v222, v222, -2.0, 1.0
	v_add_f32_e32 v222, 1.0, v222
	v_mul_f32_e32 v193, v179, v222
	v_lshlrev_b32_e32 v179, 16, v157
	v_mul_f32_e32 v222, 0x3d372713, v179
	v_mul_f32_e32 v222, v222, v179
	v_fma_f32 v222, v222, v179, v179
	v_mul_f32_e32 v222, 0x3f4c422a, v222
	v_add_f32_e32 v222, v222, v222
	v_mul_f32_e32 v222, 0x3fb8aa3b, v222
	v_exp_f32_e32 v222, v222
	v_mul_f32_e32 v179, 0.5, v179
	v_add_f32_e32 v222, 1.0, v222
	v_rcp_f32_e32 v222, v222
	s_nop 0
	v_fma_f32 v222, v222, -2.0, 1.0
	v_add_f32_e32 v222, 1.0, v222
	v_mul_f32_e32 v194, v179, v222
	v_lshlrev_b32_e32 v179, 16, v156
	v_mul_f32_e32 v222, 0x3d372713, v179
	v_mul_f32_e32 v222, v222, v179
	v_fma_f32 v222, v222, v179, v179
	v_mul_f32_e32 v222, 0x3f4c422a, v222
	v_add_f32_e32 v222, v222, v222
	v_mul_f32_e32 v222, 0x3fb8aa3b, v222
	v_exp_f32_e32 v222, v222
	v_mul_f32_e32 v179, 0.5, v179
	v_add_f32_e32 v222, 1.0, v222
	v_rcp_f32_e32 v222, v222
	s_nop 0
	v_fma_f32 v222, v222, -2.0, 1.0
	v_add_f32_e32 v222, 1.0, v222
	v_mul_f32_e32 v195, v179, v222
	s_load_dword s77, s[78:79], 0x0
	v_lshlrev_b32_e32 v226, 16, v6
	v_and_b32_e32 v227, 0xffff0000, v6
	v_pk_fma_f32 v[226:227], v[26:27], v[226:227], v[30:31]
	v_lshlrev_b32_e32 v228, 16, v2
	v_and_b32_e32 v229, 0xffff0000, v2
	v_pk_fma_f32 v[226:227], v[38:39], v[228:229], v[226:227]
	v_lshlrev_b32_e32 v228, 16, v10
	v_and_b32_e32 v229, 0xffff0000, v10
	v_pk_fma_f32 v[226:227], v[46:47], v[228:229], v[226:227]
	v_lshlrev_b32_e32 v228, 16, v14
	v_and_b32_e32 v229, 0xffff0000, v14
	v_pk_fma_f32 v[226:227], v[54:55], v[228:229], v[226:227]
	v_lshlrev_b32_e32 v228, 16, v7
	v_and_b32_e32 v229, 0xffff0000, v7
	v_pk_fma_f32 v[228:229], v[28:29], v[228:229], v[32:33]
	v_lshlrev_b32_e32 v230, 16, v3
	v_and_b32_e32 v231, 0xffff0000, v3
	v_pk_fma_f32 v[228:229], v[40:41], v[230:231], v[228:229]
	v_lshlrev_b32_e32 v230, 16, v11
	v_and_b32_e32 v231, 0xffff0000, v11
	v_pk_fma_f32 v[228:229], v[48:49], v[230:231], v[228:229]
	v_lshlrev_b32_e32 v230, 16, v15
	v_and_b32_e32 v231, 0xffff0000, v15
	v_pk_fma_f32 v[228:229], v[56:57], v[230:231], v[228:229]
	v_lshlrev_b32_e32 v230, 16, v8
	v_and_b32_e32 v231, 0xffff0000, v8
	v_pk_fma_f32 v[230:231], v[18:19], v[230:231], v[22:23]
	v_lshlrev_b32_e32 v232, 16, v4
	v_and_b32_e32 v233, 0xffff0000, v4
	v_pk_fma_f32 v[230:231], v[34:35], v[232:233], v[230:231]
	v_lshlrev_b32_e32 v232, 16, v12
	v_and_b32_e32 v233, 0xffff0000, v12
	v_pk_fma_f32 v[230:231], v[42:43], v[232:233], v[230:231]
	v_lshlrev_b32_e32 v232, 16, v16
	v_and_b32_e32 v233, 0xffff0000, v16
	v_pk_fma_f32 v[230:231], v[50:51], v[232:233], v[230:231]
	v_lshlrev_b32_e32 v232, 16, v9
	v_and_b32_e32 v233, 0xffff0000, v9
	v_pk_fma_f32 v[232:233], v[20:21], v[232:233], v[24:25]
	v_lshlrev_b32_e32 v234, 16, v5
	v_and_b32_e32 v235, 0xffff0000, v5
	v_pk_fma_f32 v[232:233], v[36:37], v[234:235], v[232:233]
	v_lshlrev_b32_e32 v234, 16, v13
	v_and_b32_e32 v235, 0xffff0000, v13
	v_pk_fma_f32 v[232:233], v[44:45], v[234:235], v[232:233]
	v_lshlrev_b32_e32 v234, 16, v17
	v_and_b32_e32 v235, 0xffff0000, v17
	v_pk_fma_f32 v[232:233], v[52:53], v[234:235], v[232:233]
	v_cvt_pk_bf16_f32 v234, v226, v227
	v_cvt_pk_bf16_f32 v235, v228, v229
	v_cvt_pk_bf16_f32 v236, v230, v231
	v_add_u32_e32 v238, v122, v90
	v_cvt_pk_bf16_f32 v237, v232, v233
	ds_write_b128 v238, v[234:237]
	ds_write_b128 v123, v[226:229] offset:9216
	ds_write_b128 v123, v[230:233] offset:9232
	s_and_saveexec_b64 s[68:69], s[44:45]
	s_cbranch_execnz .LBB0_341

.LBB0_340:
	s_or_b64 exec, exec, s[0:1]
	s_waitcnt vmcnt(0)
	v_lshlrev_b32_e32 v179, 16, v101
	v_mul_f32_e32 v222, 0x3d372713, v179
	v_mul_f32_e32 v222, v222, v179
	v_fma_f32 v222, v222, v179, v179
	v_mul_f32_e32 v222, 0x3f4c422a, v222
	v_add_f32_e32 v222, v222, v222
	v_mul_f32_e32 v222, 0x3fb8aa3b, v222
	v_exp_f32_e32 v222, v222
	v_mul_f32_e32 v179, 0.5, v179
	v_add_f32_e32 v222, 1.0, v222
	v_rcp_f32_e32 v222, v222
	s_nop 0
	v_fma_f32 v222, v222, -2.0, 1.0
	v_add_f32_e32 v222, 1.0, v222
	v_mul_f32_e32 v188, v179, v222
	v_lshlrev_b32_e32 v179, 16, v162
	v_mul_f32_e32 v222, 0x3d372713, v179
	v_mul_f32_e32 v222, v222, v179
	v_fma_f32 v222, v222, v179, v179
	v_mul_f32_e32 v222, 0x3f4c422a, v222
	v_add_f32_e32 v222, v222, v222
	v_mul_f32_e32 v222, 0x3fb8aa3b, v222
	v_exp_f32_e32 v222, v222
	v_mul_f32_e32 v179, 0.5, v179
	v_add_f32_e32 v222, 1.0, v222
	v_rcp_f32_e32 v222, v222
	s_nop 0
	v_fma_f32 v222, v222, -2.0, 1.0
	v_add_f32_e32 v222, 1.0, v222
	v_mul_f32_e32 v189, v179, v222
	v_lshlrev_b32_e32 v179, 16, v161
	v_mul_f32_e32 v222, 0x3d372713, v179
	v_mul_f32_e32 v222, v222, v179
	v_fma_f32 v222, v222, v179, v179
	v_mul_f32_e32 v222, 0x3f4c422a, v222
	v_add_f32_e32 v222, v222, v222
	v_mul_f32_e32 v222, 0x3fb8aa3b, v222
	v_exp_f32_e32 v222, v222
	v_mul_f32_e32 v179, 0.5, v179
	v_add_f32_e32 v222, 1.0, v222
	v_rcp_f32_e32 v222, v222
	s_nop 0
	v_fma_f32 v222, v222, -2.0, 1.0
	v_add_f32_e32 v222, 1.0, v222
	v_mul_f32_e32 v190, v179, v222
	v_lshlrev_b32_e32 v179, 16, v160
	v_mul_f32_e32 v222, 0x3d372713, v179
	v_mul_f32_e32 v222, v222, v179
	v_fma_f32 v222, v222, v179, v179
	v_mul_f32_e32 v222, 0x3f4c422a, v222
	v_add_f32_e32 v222, v222, v222
	v_mul_f32_e32 v222, 0x3fb8aa3b, v222
	v_exp_f32_e32 v222, v222
	v_mul_f32_e32 v179, 0.5, v179
	v_add_f32_e32 v222, 1.0, v222
	v_rcp_f32_e32 v222, v222
	s_nop 0
	v_fma_f32 v222, v222, -2.0, 1.0
	v_add_f32_e32 v222, 1.0, v222
	v_mul_f32_e32 v191, v179, v222
	v_lshlrev_b32_e32 v179, 16, v159
	v_mul_f32_e32 v222, 0x3d372713, v179
	v_mul_f32_e32 v222, v222, v179
	v_fma_f32 v222, v222, v179, v179
	v_mul_f32_e32 v222, 0x3f4c422a, v222
	v_add_f32_e32 v222, v222, v222
	v_mul_f32_e32 v222, 0x3fb8aa3b, v222
	v_exp_f32_e32 v222, v222
	v_mul_f32_e32 v179, 0.5, v179
	v_add_f32_e32 v222, 1.0, v222
	v_rcp_f32_e32 v222, v222
	s_nop 0
	v_fma_f32 v222, v222, -2.0, 1.0
	v_add_f32_e32 v222, 1.0, v222
	v_mul_f32_e32 v192, v179, v222
	v_lshlrev_b32_e32 v179, 16, v158
	v_mul_f32_e32 v222, 0x3d372713, v179
	v_mul_f32_e32 v222, v222, v179
	v_fma_f32 v222, v222, v179, v179
	v_mul_f32_e32 v222, 0x3f4c422a, v222
	v_add_f32_e32 v222, v222, v222
	v_mul_f32_e32 v222, 0x3fb8aa3b, v222
	v_exp_f32_e32 v222, v222
	v_mul_f32_e32 v179, 0.5, v179
	v_add_f32_e32 v222, 1.0, v222
	v_rcp_f32_e32 v222, v222
	s_nop 0
	v_fma_f32 v222, v222, -2.0, 1.0
	v_add_f32_e32 v222, 1.0, v222
	v_mul_f32_e32 v193, v179, v222
	v_lshlrev_b32_e32 v179, 16, v157
	v_mul_f32_e32 v222, 0x3d372713, v179
	v_mul_f32_e32 v222, v222, v179
	v_fma_f32 v222, v222, v179, v179
	v_mul_f32_e32 v222, 0x3f4c422a, v222
	v_add_f32_e32 v222, v222, v222
	v_mul_f32_e32 v222, 0x3fb8aa3b, v222
	v_exp_f32_e32 v222, v222
	v_mul_f32_e32 v179, 0.5, v179
	v_add_f32_e32 v222, 1.0, v222
	v_rcp_f32_e32 v222, v222
	s_nop 0
	v_fma_f32 v222, v222, -2.0, 1.0
	v_add_f32_e32 v222, 1.0, v222
	v_mul_f32_e32 v194, v179, v222
	v_lshlrev_b32_e32 v179, 16, v156
	v_mul_f32_e32 v222, 0x3d372713, v179
	v_mul_f32_e32 v222, v222, v179
	v_fma_f32 v222, v222, v179, v179
	v_mul_f32_e32 v222, 0x3f4c422a, v222
	v_add_f32_e32 v222, v222, v222
	v_mul_f32_e32 v222, 0x3fb8aa3b, v222
	v_exp_f32_e32 v222, v222
	v_mul_f32_e32 v179, 0.5, v179
	v_add_f32_e32 v222, 1.0, v222
	v_rcp_f32_e32 v222, v222
	s_nop 0
	v_fma_f32 v222, v222, -2.0, 1.0
	v_add_f32_e32 v222, 1.0, v222
	v_mul_f32_e32 v195, v179, v222
	s_load_dword s77, s[78:79], 0x0
	v_lshlrev_b32_e32 v226, 16, v6
	v_and_b32_e32 v227, 0xffff0000, v6
	v_pk_fma_f32 v[226:227], v[26:27], v[226:227], v[30:31]
	v_lshlrev_b32_e32 v228, 16, v2
	v_and_b32_e32 v229, 0xffff0000, v2
	v_pk_fma_f32 v[226:227], v[38:39], v[228:229], v[226:227]
	v_lshlrev_b32_e32 v228, 16, v10
	v_and_b32_e32 v229, 0xffff0000, v10
	v_pk_fma_f32 v[226:227], v[46:47], v[228:229], v[226:227]
	v_lshlrev_b32_e32 v228, 16, v14
	v_and_b32_e32 v229, 0xffff0000, v14
	v_pk_fma_f32 v[226:227], v[54:55], v[228:229], v[226:227]
	v_lshlrev_b32_e32 v228, 16, v7
	v_and_b32_e32 v229, 0xffff0000, v7
	v_pk_fma_f32 v[228:229], v[28:29], v[228:229], v[32:33]
	v_lshlrev_b32_e32 v230, 16, v3
	v_and_b32_e32 v231, 0xffff0000, v3
	v_pk_fma_f32 v[228:229], v[40:41], v[230:231], v[228:229]
	v_lshlrev_b32_e32 v230, 16, v11
	v_and_b32_e32 v231, 0xffff0000, v11
	v_pk_fma_f32 v[228:229], v[48:49], v[230:231], v[228:229]
	v_lshlrev_b32_e32 v230, 16, v15
	v_and_b32_e32 v231, 0xffff0000, v15
	v_pk_fma_f32 v[228:229], v[56:57], v[230:231], v[228:229]
	v_lshlrev_b32_e32 v230, 16, v8
	v_and_b32_e32 v231, 0xffff0000, v8
	v_pk_fma_f32 v[230:231], v[18:19], v[230:231], v[22:23]
	v_lshlrev_b32_e32 v232, 16, v4
	v_and_b32_e32 v233, 0xffff0000, v4
	v_pk_fma_f32 v[230:231], v[34:35], v[232:233], v[230:231]
	v_lshlrev_b32_e32 v232, 16, v12
	v_and_b32_e32 v233, 0xffff0000, v12
	v_pk_fma_f32 v[230:231], v[42:43], v[232:233], v[230:231]
	v_lshlrev_b32_e32 v232, 16, v16
	v_and_b32_e32 v233, 0xffff0000, v16
	v_pk_fma_f32 v[230:231], v[50:51], v[232:233], v[230:231]
	v_lshlrev_b32_e32 v232, 16, v9
	v_and_b32_e32 v233, 0xffff0000, v9
	v_pk_fma_f32 v[232:233], v[20:21], v[232:233], v[24:25]
	v_lshlrev_b32_e32 v234, 16, v5
	v_and_b32_e32 v235, 0xffff0000, v5
	v_pk_fma_f32 v[232:233], v[36:37], v[234:235], v[232:233]
	v_lshlrev_b32_e32 v234, 16, v13
	v_and_b32_e32 v235, 0xffff0000, v13
	v_pk_fma_f32 v[232:233], v[44:45], v[234:235], v[232:233]
	v_lshlrev_b32_e32 v234, 16, v17
	v_and_b32_e32 v235, 0xffff0000, v17
	v_pk_fma_f32 v[232:233], v[52:53], v[234:235], v[232:233]
	v_cvt_pk_bf16_f32 v234, v226, v227
	v_cvt_pk_bf16_f32 v235, v228, v229
	v_cvt_pk_bf16_f32 v236, v230, v231
	v_add_u32_e32 v238, v122, v90
	v_cvt_pk_bf16_f32 v237, v232, v233
	ds_write_b128 v238, v[234:237]
	ds_write_b128 v123, v[226:229] offset:9216
	ds_write_b128 v123, v[230:233] offset:9232
	s_and_saveexec_b64 s[68:69], s[44:45]
	s_cbranch_execz .LBB0_333
